# EpiSwiglu row-norm: one ss quad per lane + permlane16/32 cross-lane sum (8 loads per wave-tile instead of 32), on top of EpiResid prefetch
# baseline (speedup 1.0000x reference)
; __device__ __forceinline__ float sigmoidf_(float x) { return __builtin_amdgcn_rcpf(1.f + __expf(-x)); }
; __device__ __forceinline__ u32x2 pack4(const f32x4& a) { u32x2 w; w.x = pk2(a[0], a[1]); w.y = pk2(a[2], a[3]); return w; }
; #define EPI_LOOP_ROWS for (int am_ = 0; am_ < 8; ++am_)
; __device__ __forceinline__ float ss_rstd(const float* ssrow) { const f32x4 a = *(const f32x4*)ssrow, b = *(const f32x4*)(ssrow + 4), c = *(const f32x4*)(ssrow + 8), d = *(const f32x4*)(ssrow + 12);
;     const float s = ((a[0] + a[1]) + (a[2] + a[3])) + ((b[0] + b[1]) + (b[2] + b[3])) + ((c[0] + c[1]) + (c[2] + c[3])) + ((d[0] + d[1]) + (d[2] + d[3])); return rsqrtf(s * (1.f / D) + 1e-6f); }
;     __device__ __forceinline__ void operator()(const f32x4 (&acc)[2][2][4][2], const pg8::Unit& u, int wr, int wc, int fr, int fq) const { asm volatile("" : "+v"(fr), "+v"(fq));
; #pragma unroll
;         EPI_LOOP_ROWS { EPI_AM const int row = u.pm * 256 + ai * 128 + wr * 64 + m * 16 + fr; const float rstd = ss_rstd(ss + (size_t)row * 16);
; #pragma unroll
;             for (int bj = 0; bj < 2; ++bj) { const int col0 = u.pn * 256 + bj * 128 + wc * 32 + 8 * fq; const f32x4 g = acc[ai][bj][m][0] * rstd, up = acc[ai][bj][m][1] * rstd; f32x4 o;
; #pragma unroll
;                 for (int j = 0; j < 4; ++j) o[j] = g[j] * sigmoidf_(g[j]) * up[j];
;                 *(u32x2*)(act + (size_t)row * FF + (col0 >> 1)) = pack4(o); } }
.LBB0_191:
	v_mov_b32_e32 v139, v148
	v_mov_b32_e32 v142, v149
	s_lshl_b32 s33, s33, 8
	s_add_i32 s33, s33, s71
	v_add_u32_e32 v142, s33, v142
	v_ashrrev_i32_e32 v143, 31, v142
	s_lshl_b32 s33, s80, 8
	s_or_b32 s33, s33, s74
	v_lshl_add_u32 v139, v139, 3, s33
	v_lshlrev_b64 v[228:229], 6, v[142:143]
	v_lshl_add_u64 v[228:229], s[16:17], 0, v[228:229]
	v_and_b32_e32 v174, 0x30, v166
	v_mov_b32_e32 v175, 0
	v_lshl_add_u64 v[228:229], v[174:175], 0, v[228:229]
	v_add_co_u32_e32 v172, vcc, 0x2000, v228
	s_nop 1
	v_addc_co_u32_e32 v173, vcc, 0, v229, vcc
	global_load_dwordx4 v[176:179], v[228:229], off offset:0
	global_load_dwordx4 v[180:183], v[228:229], off offset:1024
	global_load_dwordx4 v[184:187], v[228:229], off offset:2048
	global_load_dwordx4 v[188:191], v[228:229], off offset:3072
	global_load_dwordx4 v[192:195], v[172:173], off offset:0
	global_load_dwordx4 v[196:199], v[172:173], off offset:1024
	global_load_dwordx4 v[200:203], v[172:173], off offset:2048
	global_load_dwordx4 v[204:207], v[172:173], off offset:3072
	s_waitcnt vmcnt(0)
	v_add_f32_e32 v176, v176, v177
	v_add_f32_e32 v180, v180, v181
	v_add_f32_e32 v184, v184, v185
	v_add_f32_e32 v188, v188, v189
	v_add_f32_e32 v192, v192, v193
	v_add_f32_e32 v196, v196, v197
	v_add_f32_e32 v200, v200, v201
	v_add_f32_e32 v204, v204, v205
	v_add_f32_e32 v178, v178, v179
	v_add_f32_e32 v182, v182, v183
	v_add_f32_e32 v186, v186, v187
	v_add_f32_e32 v190, v190, v191
	v_add_f32_e32 v194, v194, v195
	v_add_f32_e32 v198, v198, v199
	v_add_f32_e32 v202, v202, v203
	v_add_f32_e32 v206, v206, v207
	v_add_f32_e32 v176, v176, v178
	v_add_f32_e32 v180, v180, v182
	v_add_f32_e32 v184, v184, v186
	v_add_f32_e32 v188, v188, v190
	v_add_f32_e32 v192, v192, v194
	v_add_f32_e32 v196, v196, v198
	v_add_f32_e32 v200, v200, v202
	v_add_f32_e32 v204, v204, v206
	v_mov_b32_e32 v177, v176
	v_mov_b32_e32 v181, v180
	v_mov_b32_e32 v185, v184
	v_mov_b32_e32 v189, v188
	v_mov_b32_e32 v193, v192
	v_mov_b32_e32 v197, v196
	v_mov_b32_e32 v201, v200
	v_mov_b32_e32 v205, v204
	v_permlane16_swap_b32 v176, v177
	v_permlane16_swap_b32 v180, v181
	v_permlane16_swap_b32 v184, v185
	v_permlane16_swap_b32 v188, v189
	v_permlane16_swap_b32 v192, v193
	v_permlane16_swap_b32 v196, v197
	v_permlane16_swap_b32 v200, v201
	v_permlane16_swap_b32 v204, v205
	v_add_f32_e32 v176, v176, v177
	v_add_f32_e32 v180, v180, v181
	v_add_f32_e32 v184, v184, v185
	v_add_f32_e32 v188, v188, v189
	v_add_f32_e32 v192, v192, v193
	v_add_f32_e32 v196, v196, v197
	v_add_f32_e32 v200, v200, v201
	v_add_f32_e32 v204, v204, v205
	v_mov_b32_e32 v177, v176
	v_mov_b32_e32 v181, v180
	v_mov_b32_e32 v185, v184
	v_mov_b32_e32 v189, v188
	v_mov_b32_e32 v193, v192
	v_mov_b32_e32 v197, v196
	v_mov_b32_e32 v201, v200
	v_mov_b32_e32 v205, v204
	v_permlane32_swap_b32 v176, v177
	v_permlane32_swap_b32 v180, v181
	v_permlane32_swap_b32 v184, v185
	v_permlane32_swap_b32 v188, v189
	v_permlane32_swap_b32 v192, v193
	v_permlane32_swap_b32 v196, v197
	v_permlane32_swap_b32 v200, v201
	v_permlane32_swap_b32 v204, v205
	v_add_f32_e32 v176, v176, v177
	v_add_f32_e32 v180, v180, v181
	v_add_f32_e32 v184, v184, v185
	v_add_f32_e32 v188, v188, v189
	v_add_f32_e32 v192, v192, v193
	v_add_f32_e32 v196, v196, v197
	v_add_f32_e32 v200, v200, v201
	v_add_f32_e32 v204, v204, v205
	v_fmamk_f32 v176, v176, 0x3a800000, v138
	v_cmp_gt_f32_e32 vcc, s64, v176
	v_mul_f32_e32 v177, 0x4b800000, v176
	s_nop 0
	v_cndmask_b32_e32 v176, v176, v177, vcc
	v_rsq_f32_e32 v176, v176
	s_nop 0
	v_mul_f32_e32 v177, 0x45800000, v176
	v_cndmask_b32_e32 v246, v176, v177, vcc
	v_fmamk_f32 v180, v180, 0x3a800000, v138
	v_cmp_gt_f32_e32 vcc, s64, v180
	v_mul_f32_e32 v181, 0x4b800000, v180
	s_nop 0
	v_cndmask_b32_e32 v180, v180, v181, vcc
	v_rsq_f32_e32 v180, v180
	s_nop 0
	v_mul_f32_e32 v181, 0x45800000, v180
	v_cndmask_b32_e32 v247, v180, v181, vcc
	v_fmamk_f32 v184, v184, 0x3a800000, v138
	v_cmp_gt_f32_e32 vcc, s64, v184
	v_mul_f32_e32 v185, 0x4b800000, v184
	s_nop 0
	v_cndmask_b32_e32 v184, v184, v185, vcc
	v_rsq_f32_e32 v184, v184
	s_nop 0
	v_mul_f32_e32 v185, 0x45800000, v184
	v_cndmask_b32_e32 v248, v184, v185, vcc
	v_fmamk_f32 v188, v188, 0x3a800000, v138
	v_cmp_gt_f32_e32 vcc, s64, v188
	v_mul_f32_e32 v189, 0x4b800000, v188
	s_nop 0
	v_cndmask_b32_e32 v188, v188, v189, vcc
	v_rsq_f32_e32 v188, v188
	s_nop 0
	v_mul_f32_e32 v189, 0x45800000, v188
	v_cndmask_b32_e32 v249, v188, v189, vcc
	v_fmamk_f32 v192, v192, 0x3a800000, v138
	v_cmp_gt_f32_e32 vcc, s64, v192
	v_mul_f32_e32 v193, 0x4b800000, v192
	s_nop 0
	v_cndmask_b32_e32 v192, v192, v193, vcc
	v_rsq_f32_e32 v192, v192
	s_nop 0
	v_mul_f32_e32 v193, 0x45800000, v192
	v_cndmask_b32_e32 v250, v192, v193, vcc
	v_fmamk_f32 v196, v196, 0x3a800000, v138
	v_cmp_gt_f32_e32 vcc, s64, v196
	v_mul_f32_e32 v197, 0x4b800000, v196
	s_nop 0
	v_cndmask_b32_e32 v196, v196, v197, vcc
	v_rsq_f32_e32 v196, v196
	s_nop 0
	v_mul_f32_e32 v197, 0x45800000, v196
	v_cndmask_b32_e32 v251, v196, v197, vcc
	v_fmamk_f32 v200, v200, 0x3a800000, v138
	v_cmp_gt_f32_e32 vcc, s64, v200
	v_mul_f32_e32 v201, 0x4b800000, v200
	s_nop 0
	v_cndmask_b32_e32 v200, v200, v201, vcc
	v_rsq_f32_e32 v200, v200
	s_nop 0
	v_mul_f32_e32 v201, 0x45800000, v200
	v_cndmask_b32_e32 v252, v200, v201, vcc
	v_fmamk_f32 v204, v204, 0x3a800000, v138
	v_cmp_gt_f32_e32 vcc, s64, v204
	v_mul_f32_e32 v205, 0x4b800000, v204
	s_nop 0
	v_cndmask_b32_e32 v204, v204, v205, vcc
	v_rsq_f32_e32 v204, v204
	s_nop 0
	v_mul_f32_e32 v205, 0x45800000, v204
	v_cndmask_b32_e32 v253, v204, v205, vcc
	v_mov_b32_e32 v144, v246
	v_pk_mul_f32 v[124:125], v[124:125], v[144:145] op_sel_hi:[1,0]
	v_pk_mul_f32 v[120:121], v[120:121], v[144:145] op_sel_hi:[1,0]
; __device__ __forceinline__ float sigmoidf_(float x) { return __builtin_amdgcn_rcpf(1.f + __expf(-x)); }
; __device__ __forceinline__ u32x2 pack4(const f32x4& a) { u32x2 w; w.x = pk2(a[0], a[1]); w.y = pk2(a[2], a[3]); return w; }
; #define EPI_LOOP_ROWS for (int am_ = 0; am_ < 8; ++am_)
;     __device__ __forceinline__ void operator()(const f32x4 (&acc)[2][2][4][2], const pg8::Unit& u, int wr, int wc, int fr, int fq) const { asm volatile("" : "+v"(fr), "+v"(fq));
;     ...
;         EPI_LOOP_ROWS { EPI_AM const int row = u.pm * 256 + ai * 128 + wr * 64 + m * 16 + fr; const float rstd = ss_rstd(ss + (size_t)row * 16);
; #pragma unroll
;             for (int bj = 0; bj < 2; ++bj) { const int col0 = u.pn * 256 + bj * 128 + wc * 32 + 8 * fq; const f32x4 g = acc[ai][bj][m][0] * rstd, up = acc[ai][bj][m][1] * rstd; f32x4 o;
; #pragma unroll
;                 for (int j = 0; j < 4; ++j) o[j] = g[j] * sigmoidf_(g[j]) * up[j];
;                 *(u32x2*)(act + (size_t)row * FF + (col0 >> 1)) = pack4(o); } }
	v_mul_f32_e32 v143, 0xbfb8aa3b, v124
	v_exp_f32_e32 v143, v143
	v_pk_mul_f32 v[122:123], v[122:123], v[144:145] op_sel_hi:[1,0]
	v_pk_mul_f32 v[116:117], v[116:117], v[144:145] op_sel_hi:[1,0]
	v_pk_mul_f32 v[112:113], v[112:113], v[144:145] op_sel_hi:[1,0]
	v_add_f32_e32 v143, 1.0, v143
	v_rcp_f32_e32 v146, v143
	v_mul_f32_e32 v143, 0xbfb8aa3b, v125
	v_exp_f32_e32 v143, v143
	v_pk_mul_f32 v[114:115], v[114:115], v[144:145] op_sel_hi:[1,0]
	v_add_f32_e32 v143, 1.0, v143
	v_rcp_f32_e32 v147, v143
	s_nop 0
	v_pk_mul_f32 v[124:125], v[124:125], v[146:147]
	s_nop 0
	v_pk_mul_f32 v[120:121], v[120:121], v[124:125]
	v_pk_mul_f32 v[124:125], v[126:127], v[144:145] op_sel_hi:[1,0]
	v_cvt_pk_bf16_f32 v120, v120, v121
	v_mul_f32_e32 v126, 0xbfb8aa3b, v124
	v_mul_f32_e32 v127, 0xbfb8aa3b, v125
	v_exp_f32_e32 v126, v126
	v_exp_f32_e32 v127, v127
	v_add_f32_e32 v126, 1.0, v126
	v_add_f32_e32 v127, 1.0, v127
	v_rcp_f32_e32 v126, v126
	v_rcp_f32_e32 v127, v127
	s_nop 0
	v_pk_mul_f32 v[124:125], v[124:125], v[126:127]
	v_ashrrev_i32_e32 v126, 1, v139
	v_pk_mul_f32 v[122:123], v[122:123], v[124:125]
	v_mov_b64_e32 v[124:125], s[88:89]
	v_ashrrev_i32_e32 v127, 31, v126
	v_cvt_pk_bf16_f32 v121, v122, v123
	v_mad_i64_i32 v[122:123], s[38:39], v142, s59, v[124:125]
	v_lshlrev_b64 v[126:127], 1, v[126:127]
	v_lshl_add_u64 v[146:147], v[122:123], 0, v[126:127]
	global_store_dwordx2 v[146:147], v[120:121], off
	v_mul_f32_e32 v120, 0xbfb8aa3b, v116
	v_mul_f32_e32 v121, 0xbfb8aa3b, v117
	v_exp_f32_e32 v120, v120
	v_exp_f32_e32 v121, v121
	v_add_u32_e32 v146, 16, v142
	v_ashrrev_i32_e32 v147, 31, v146
	v_add_f32_e32 v120, 1.0, v120
	v_add_f32_e32 v121, 1.0, v121
	v_rcp_f32_e32 v120, v120
	v_rcp_f32_e32 v121, v121
	s_nop 0
	v_pk_mul_f32 v[116:117], v[116:117], v[120:121]
	s_nop 0
	v_pk_mul_f32 v[112:113], v[112:113], v[116:117]
	v_pk_mul_f32 v[116:117], v[118:119], v[144:145] op_sel_hi:[1,0]
	v_cvt_pk_bf16_f32 v112, v112, v113
	v_mul_f32_e32 v118, 0xbfb8aa3b, v116
	v_mul_f32_e32 v119, 0xbfb8aa3b, v117
	v_exp_f32_e32 v118, v118
	v_exp_f32_e32 v119, v119
	v_add_f32_e32 v118, 1.0, v118
	v_add_f32_e32 v119, 1.0, v119
	v_rcp_f32_e32 v118, v118
	v_rcp_f32_e32 v119, v119
	s_nop 0
	v_pk_mul_f32 v[116:117], v[116:117], v[118:119]
	s_nop 0
	v_pk_mul_f32 v[114:115], v[114:115], v[116:117]
	v_add_u32_e32 v116, 0x80, v139
	v_cvt_pk_bf16_f32 v113, v114, v115
	v_ashrrev_i32_e32 v114, 1, v116
	v_ashrrev_i32_e32 v115, 31, v114
	v_lshlrev_b64 v[144:145], 1, v[114:115]
	v_lshl_add_u64 v[114:115], v[122:123], 0, v[144:145]
	global_store_dwordx2 v[114:115], v[112:113], off
	v_mov_b32_e32 v112, v247
	v_pk_mul_f32 v[108:109], v[108:109], v[112:113] op_sel_hi:[1,0]
	s_nop 0
	v_mul_f32_e32 v113, 0xbfb8aa3b, v108
	v_exp_f32_e32 v113, v113
	s_nop 0
	v_add_f32_e32 v113, 1.0, v113
	v_rcp_f32_e32 v114, v113
	v_mul_f32_e32 v113, 0xbfb8aa3b, v109
	v_exp_f32_e32 v113, v113
	s_nop 0
	v_add_f32_e32 v113, 1.0, v113
	v_rcp_f32_e32 v115, v113
	v_pk_mul_f32 v[104:105], v[104:105], v[112:113] op_sel_hi:[1,0]
	v_pk_mul_f32 v[106:107], v[106:107], v[112:113] op_sel_hi:[1,0]
	v_pk_mul_f32 v[100:101], v[100:101], v[112:113] op_sel_hi:[1,0]
	v_pk_mul_f32 v[108:109], v[108:109], v[114:115]
	v_pk_mul_f32 v[96:97], v[96:97], v[112:113] op_sel_hi:[1,0]
	v_pk_mul_f32 v[104:105], v[104:105], v[108:109]
	v_pk_mul_f32 v[108:109], v[110:111], v[112:113] op_sel_hi:[1,0]
	v_cvt_pk_bf16_f32 v104, v104, v105
	v_mul_f32_e32 v110, 0xbfb8aa3b, v108
	v_mul_f32_e32 v111, 0xbfb8aa3b, v109
	v_exp_f32_e32 v110, v110
	v_exp_f32_e32 v111, v111
	v_pk_mul_f32 v[98:99], v[98:99], v[112:113] op_sel_hi:[1,0]
	v_add_f32_e32 v110, 1.0, v110
	v_add_f32_e32 v111, 1.0, v111
	v_rcp_f32_e32 v110, v110
	v_rcp_f32_e32 v111, v111
	s_nop 0
	v_pk_mul_f32 v[108:109], v[108:109], v[110:111]
	s_nop 0
	v_pk_mul_f32 v[106:107], v[106:107], v[108:109]
	s_nop 0
	v_cvt_pk_bf16_f32 v105, v106, v107
	v_mad_i64_i32 v[106:107], s[38:39], v146, s59, v[124:125]
	v_lshl_add_u64 v[108:109], v[106:107], 0, v[126:127]
	global_store_dwordx2 v[108:109], v[104:105], off
	v_mul_f32_e32 v104, 0xbfb8aa3b, v100
	v_mul_f32_e32 v105, 0xbfb8aa3b, v101
	v_exp_f32_e32 v104, v104
	v_exp_f32_e32 v105, v105
	v_add_u32_e32 v108, 32, v142
	v_ashrrev_i32_e32 v109, 31, v108
	v_add_f32_e32 v104, 1.0, v104
	v_add_f32_e32 v105, 1.0, v105
	v_rcp_f32_e32 v104, v104
	v_rcp_f32_e32 v105, v105
	s_nop 0
	v_pk_mul_f32 v[100:101], v[100:101], v[104:105]
	s_nop 0
	v_pk_mul_f32 v[96:97], v[96:97], v[100:101]
	v_pk_mul_f32 v[100:101], v[102:103], v[112:113] op_sel_hi:[1,0]
	v_cvt_pk_bf16_f32 v96, v96, v97
	v_mul_f32_e32 v102, 0xbfb8aa3b, v100
	v_mul_f32_e32 v103, 0xbfb8aa3b, v101
	v_exp_f32_e32 v102, v102
	v_exp_f32_e32 v103, v103
	v_add_f32_e32 v102, 1.0, v102
	v_add_f32_e32 v103, 1.0, v103
	v_rcp_f32_e32 v102, v102
	v_rcp_f32_e32 v103, v103
	s_nop 0
	v_pk_mul_f32 v[100:101], v[100:101], v[102:103]
	s_nop 0
	v_pk_mul_f32 v[98:99], v[98:99], v[100:101]
	s_nop 0
	v_cvt_pk_bf16_f32 v97, v98, v99
	v_lshl_add_u64 v[98:99], v[106:107], 0, v[144:145]
	global_store_dwordx2 v[98:99], v[96:97], off
	v_mov_b32_e32 v96, v248
	v_pk_mul_f32 v[92:93], v[92:93], v[96:97] op_sel_hi:[1,0]
	s_nop 0
	v_mul_f32_e32 v97, 0xbfb8aa3b, v92
	v_exp_f32_e32 v97, v97
	s_nop 0
	v_add_f32_e32 v97, 1.0, v97
	v_rcp_f32_e32 v98, v97
	v_mul_f32_e32 v97, 0xbfb8aa3b, v93
	v_exp_f32_e32 v97, v97
	s_nop 0
	v_add_f32_e32 v97, 1.0, v97
	v_rcp_f32_e32 v99, v97
	v_pk_mul_f32 v[88:89], v[88:89], v[96:97] op_sel_hi:[1,0]
	v_pk_mul_f32 v[90:91], v[90:91], v[96:97] op_sel_hi:[1,0]
	v_pk_mul_f32 v[84:85], v[84:85], v[96:97] op_sel_hi:[1,0]
	v_pk_mul_f32 v[92:93], v[92:93], v[98:99]
	v_pk_mul_f32 v[80:81], v[80:81], v[96:97] op_sel_hi:[1,0]
; __device__ __forceinline__ float sigmoidf_(float x) { return __builtin_amdgcn_rcpf(1.f + __expf(-x)); }
; __device__ __forceinline__ u32x2 pack4(const f32x4& a) { u32x2 w; w.x = pk2(a[0], a[1]); w.y = pk2(a[2], a[3]); return w; }
; #define EPI_LOOP_ROWS for (int am_ = 0; am_ < 8; ++am_)
;     __device__ __forceinline__ void operator()(const f32x4 (&acc)[2][2][4][2], const pg8::Unit& u, int wr, int wc, int fr, int fq) const { asm volatile("" : "+v"(fr), "+v"(fq));
;     ...
;         EPI_LOOP_ROWS { EPI_AM const int row = u.pm * 256 + ai * 128 + wr * 64 + m * 16 + fr; const float rstd = ss_rstd(ss + (size_t)row * 16);
; #pragma unroll
;             for (int bj = 0; bj < 2; ++bj) { const int col0 = u.pn * 256 + bj * 128 + wc * 32 + 8 * fq; const f32x4 g = acc[ai][bj][m][0] * rstd, up = acc[ai][bj][m][1] * rstd; f32x4 o;
; #pragma unroll
;                 for (int j = 0; j < 4; ++j) o[j] = g[j] * sigmoidf_(g[j]) * up[j];
;                 *(u32x2*)(act + (size_t)row * FF + (col0 >> 1)) = pack4(o); } }
	v_pk_mul_f32 v[88:89], v[88:89], v[92:93]
	v_pk_mul_f32 v[92:93], v[94:95], v[96:97] op_sel_hi:[1,0]
	v_cvt_pk_bf16_f32 v88, v88, v89
	v_mul_f32_e32 v94, 0xbfb8aa3b, v92
	v_mul_f32_e32 v95, 0xbfb8aa3b, v93
	v_exp_f32_e32 v94, v94
	v_exp_f32_e32 v95, v95
	v_pk_mul_f32 v[82:83], v[82:83], v[96:97] op_sel_hi:[1,0]
	v_add_f32_e32 v94, 1.0, v94
	v_add_f32_e32 v95, 1.0, v95
	v_rcp_f32_e32 v94, v94
	v_rcp_f32_e32 v95, v95
	s_nop 0
	v_pk_mul_f32 v[92:93], v[92:93], v[94:95]
	s_nop 0
	v_pk_mul_f32 v[90:91], v[90:91], v[92:93]
	s_nop 0
	v_cvt_pk_bf16_f32 v89, v90, v91
	v_mad_i64_i32 v[90:91], s[38:39], v108, s59, v[124:125]
	v_lshl_add_u64 v[92:93], v[90:91], 0, v[126:127]
	global_store_dwordx2 v[92:93], v[88:89], off
	v_mul_f32_e32 v88, 0xbfb8aa3b, v84
	v_mul_f32_e32 v89, 0xbfb8aa3b, v85
	v_exp_f32_e32 v88, v88
	v_exp_f32_e32 v89, v89
	v_add_u32_e32 v92, 48, v142
	v_ashrrev_i32_e32 v93, 31, v92
	v_add_f32_e32 v88, 1.0, v88
	v_add_f32_e32 v89, 1.0, v89
	v_rcp_f32_e32 v88, v88
	v_rcp_f32_e32 v89, v89
	s_nop 0
	v_pk_mul_f32 v[84:85], v[84:85], v[88:89]
	s_nop 0
	v_pk_mul_f32 v[80:81], v[80:81], v[84:85]
	v_pk_mul_f32 v[84:85], v[86:87], v[96:97] op_sel_hi:[1,0]
	v_cvt_pk_bf16_f32 v80, v80, v81
	v_mul_f32_e32 v86, 0xbfb8aa3b, v84
	v_mul_f32_e32 v87, 0xbfb8aa3b, v85
	v_exp_f32_e32 v86, v86
	v_exp_f32_e32 v87, v87
	v_add_f32_e32 v86, 1.0, v86
	v_add_f32_e32 v87, 1.0, v87
	v_rcp_f32_e32 v86, v86
	v_rcp_f32_e32 v87, v87
	s_nop 0
	v_pk_mul_f32 v[84:85], v[84:85], v[86:87]
	s_nop 0
	v_pk_mul_f32 v[82:83], v[82:83], v[84:85]
	s_nop 0
	v_cvt_pk_bf16_f32 v81, v82, v83
	v_lshl_add_u64 v[82:83], v[90:91], 0, v[144:145]
	global_store_dwordx2 v[82:83], v[80:81], off
	v_mov_b32_e32 v80, v249
	v_pk_mul_f32 v[76:77], v[76:77], v[80:81] op_sel_hi:[1,0]
	s_nop 0
	v_mul_f32_e32 v81, 0xbfb8aa3b, v76
	v_exp_f32_e32 v81, v81
	s_nop 0
	v_add_f32_e32 v81, 1.0, v81
	v_rcp_f32_e32 v82, v81
	v_mul_f32_e32 v81, 0xbfb8aa3b, v77
	v_exp_f32_e32 v81, v81
	s_nop 0
	v_add_f32_e32 v81, 1.0, v81
	v_rcp_f32_e32 v83, v81
	v_pk_mul_f32 v[72:73], v[72:73], v[80:81] op_sel_hi:[1,0]
	v_pk_mul_f32 v[74:75], v[74:75], v[80:81] op_sel_hi:[1,0]
	v_pk_mul_f32 v[68:69], v[68:69], v[80:81] op_sel_hi:[1,0]
	v_pk_mul_f32 v[76:77], v[76:77], v[82:83]
	v_pk_mul_f32 v[64:65], v[64:65], v[80:81] op_sel_hi:[1,0]
	v_pk_mul_f32 v[72:73], v[72:73], v[76:77]
	v_pk_mul_f32 v[76:77], v[78:79], v[80:81] op_sel_hi:[1,0]
	v_cvt_pk_bf16_f32 v72, v72, v73
	v_mul_f32_e32 v78, 0xbfb8aa3b, v76
	v_mul_f32_e32 v79, 0xbfb8aa3b, v77
	v_exp_f32_e32 v78, v78
	v_exp_f32_e32 v79, v79
	v_pk_mul_f32 v[66:67], v[66:67], v[80:81] op_sel_hi:[1,0]
	v_add_f32_e32 v78, 1.0, v78
	v_add_f32_e32 v79, 1.0, v79
	v_rcp_f32_e32 v78, v78
	v_rcp_f32_e32 v79, v79
	s_nop 0
	v_pk_mul_f32 v[76:77], v[76:77], v[78:79]
	s_nop 0
	v_pk_mul_f32 v[74:75], v[74:75], v[76:77]
	s_nop 0
	v_cvt_pk_bf16_f32 v73, v74, v75
	v_mad_i64_i32 v[74:75], s[38:39], v92, s59, v[124:125]
	v_lshl_add_u64 v[76:77], v[74:75], 0, v[126:127]
	global_store_dwordx2 v[76:77], v[72:73], off
	v_mul_f32_e32 v72, 0xbfb8aa3b, v68
	v_mul_f32_e32 v73, 0xbfb8aa3b, v69
	v_exp_f32_e32 v72, v72
	v_exp_f32_e32 v73, v73
	v_add_u32_e32 v76, 0x80, v142
	v_ashrrev_i32_e32 v77, 31, v76
	v_add_f32_e32 v72, 1.0, v72
	v_add_f32_e32 v73, 1.0, v73
	v_rcp_f32_e32 v72, v72
	v_rcp_f32_e32 v73, v73
	s_nop 0
	v_pk_mul_f32 v[68:69], v[68:69], v[72:73]
	s_nop 0
	v_pk_mul_f32 v[64:65], v[64:65], v[68:69]
	v_pk_mul_f32 v[68:69], v[70:71], v[80:81] op_sel_hi:[1,0]
	v_cvt_pk_bf16_f32 v64, v64, v65
	v_mul_f32_e32 v70, 0xbfb8aa3b, v68
	v_mul_f32_e32 v71, 0xbfb8aa3b, v69
	v_exp_f32_e32 v70, v70
	v_exp_f32_e32 v71, v71
	v_add_f32_e32 v70, 1.0, v70
	v_add_f32_e32 v71, 1.0, v71
	v_rcp_f32_e32 v70, v70
	v_rcp_f32_e32 v71, v71
	s_nop 0
	v_pk_mul_f32 v[68:69], v[68:69], v[70:71]
	s_nop 0
	v_pk_mul_f32 v[66:67], v[66:67], v[68:69]
	s_nop 0
	v_cvt_pk_bf16_f32 v65, v66, v67
	v_lshl_add_u64 v[66:67], v[74:75], 0, v[144:145]
	global_store_dwordx2 v[66:67], v[64:65], off
	v_mov_b32_e32 v64, v250
	v_pk_mul_f32 v[60:61], v[60:61], v[64:65] op_sel_hi:[1,0]
	s_nop 0
	v_mul_f32_e32 v65, 0xbfb8aa3b, v60
	v_exp_f32_e32 v65, v65
	s_nop 0
	v_add_f32_e32 v65, 1.0, v65
	v_rcp_f32_e32 v66, v65
	v_mul_f32_e32 v65, 0xbfb8aa3b, v61
	v_exp_f32_e32 v65, v65
	s_nop 0
	v_add_f32_e32 v65, 1.0, v65
	v_rcp_f32_e32 v67, v65
	v_pk_mul_f32 v[56:57], v[56:57], v[64:65] op_sel_hi:[1,0]
	v_pk_mul_f32 v[58:59], v[58:59], v[64:65] op_sel_hi:[1,0]
	v_pk_mul_f32 v[52:53], v[52:53], v[64:65] op_sel_hi:[1,0]
	v_pk_mul_f32 v[60:61], v[60:61], v[66:67]
	v_pk_mul_f32 v[48:49], v[48:49], v[64:65] op_sel_hi:[1,0]
	v_pk_mul_f32 v[56:57], v[56:57], v[60:61]
	v_pk_mul_f32 v[60:61], v[62:63], v[64:65] op_sel_hi:[1,0]
	v_cvt_pk_bf16_f32 v56, v56, v57
	v_mul_f32_e32 v62, 0xbfb8aa3b, v60
	v_mul_f32_e32 v63, 0xbfb8aa3b, v61
	v_exp_f32_e32 v62, v62
	v_exp_f32_e32 v63, v63
	v_pk_mul_f32 v[50:51], v[50:51], v[64:65] op_sel_hi:[1,0]
	v_add_f32_e32 v62, 1.0, v62
	v_add_f32_e32 v63, 1.0, v63
	v_rcp_f32_e32 v62, v62
	v_rcp_f32_e32 v63, v63
	s_nop 0
	v_pk_mul_f32 v[60:61], v[60:61], v[62:63]
	s_nop 0
	v_pk_mul_f32 v[58:59], v[58:59], v[60:61]
	s_nop 0
	v_cvt_pk_bf16_f32 v57, v58, v59
	v_mad_i64_i32 v[58:59], s[38:39], v76, s59, v[124:125]
	v_lshl_add_u64 v[60:61], v[58:59], 0, v[126:127]
	global_store_dwordx2 v[60:61], v[56:57], off
	v_mul_f32_e32 v56, 0xbfb8aa3b, v52
	v_mul_f32_e32 v57, 0xbfb8aa3b, v53
	v_exp_f32_e32 v56, v56
	v_exp_f32_e32 v57, v57
	v_add_u32_e32 v60, 0x90, v142
	v_ashrrev_i32_e32 v61, 31, v60
	v_add_f32_e32 v56, 1.0, v56
	v_add_f32_e32 v57, 1.0, v57
	v_rcp_f32_e32 v56, v56
	v_rcp_f32_e32 v57, v57
	s_nop 0
	v_pk_mul_f32 v[52:53], v[52:53], v[56:57]
	s_nop 0
; __device__ __forceinline__ float sigmoidf_(float x) { return __builtin_amdgcn_rcpf(1.f + __expf(-x)); }
; __device__ __forceinline__ u32x2 pack4(const f32x4& a) { u32x2 w; w.x = pk2(a[0], a[1]); w.y = pk2(a[2], a[3]); return w; }
; #define EPI_LOOP_ROWS for (int am_ = 0; am_ < 8; ++am_)
;     __device__ __forceinline__ void operator()(const f32x4 (&acc)[2][2][4][2], const pg8::Unit& u, int wr, int wc, int fr, int fq) const { asm volatile("" : "+v"(fr), "+v"(fq));
;     ...
;         EPI_LOOP_ROWS { EPI_AM const int row = u.pm * 256 + ai * 128 + wr * 64 + m * 16 + fr; const float rstd = ss_rstd(ss + (size_t)row * 16);
; #pragma unroll
;             for (int bj = 0; bj < 2; ++bj) { const int col0 = u.pn * 256 + bj * 128 + wc * 32 + 8 * fq; const f32x4 g = acc[ai][bj][m][0] * rstd, up = acc[ai][bj][m][1] * rstd; f32x4 o;
; #pragma unroll
;                 for (int j = 0; j < 4; ++j) o[j] = g[j] * sigmoidf_(g[j]) * up[j];
;                 *(u32x2*)(act + (size_t)row * FF + (col0 >> 1)) = pack4(o); } }
	v_pk_mul_f32 v[48:49], v[48:49], v[52:53]
	v_pk_mul_f32 v[52:53], v[54:55], v[64:65] op_sel_hi:[1,0]
	v_cvt_pk_bf16_f32 v48, v48, v49
	v_mul_f32_e32 v54, 0xbfb8aa3b, v52
	v_mul_f32_e32 v55, 0xbfb8aa3b, v53
	v_exp_f32_e32 v54, v54
	v_exp_f32_e32 v55, v55
	v_add_f32_e32 v54, 1.0, v54
	v_add_f32_e32 v55, 1.0, v55
	v_rcp_f32_e32 v54, v54
	v_rcp_f32_e32 v55, v55
	s_nop 0
	v_pk_mul_f32 v[52:53], v[52:53], v[54:55]
	s_nop 0
	v_pk_mul_f32 v[50:51], v[50:51], v[52:53]
	s_nop 0
	v_cvt_pk_bf16_f32 v49, v50, v51
	v_lshl_add_u64 v[50:51], v[58:59], 0, v[144:145]
	global_store_dwordx2 v[50:51], v[48:49], off
	v_mov_b32_e32 v48, v251
	v_pk_mul_f32 v[44:45], v[44:45], v[48:49] op_sel_hi:[1,0]
	s_nop 0
	v_mul_f32_e32 v49, 0xbfb8aa3b, v44
	v_exp_f32_e32 v49, v49
	s_nop 0
	v_add_f32_e32 v49, 1.0, v49
	v_rcp_f32_e32 v50, v49
	v_mul_f32_e32 v49, 0xbfb8aa3b, v45
	v_exp_f32_e32 v49, v49
	s_nop 0
	v_add_f32_e32 v49, 1.0, v49
	v_rcp_f32_e32 v51, v49
	v_pk_mul_f32 v[40:41], v[40:41], v[48:49] op_sel_hi:[1,0]
	v_pk_mul_f32 v[42:43], v[42:43], v[48:49] op_sel_hi:[1,0]
	v_pk_mul_f32 v[36:37], v[36:37], v[48:49] op_sel_hi:[1,0]
	v_pk_mul_f32 v[44:45], v[44:45], v[50:51]
	v_pk_mul_f32 v[32:33], v[32:33], v[48:49] op_sel_hi:[1,0]
	v_pk_mul_f32 v[40:41], v[40:41], v[44:45]
	v_pk_mul_f32 v[44:45], v[46:47], v[48:49] op_sel_hi:[1,0]
	v_cvt_pk_bf16_f32 v40, v40, v41
	v_mul_f32_e32 v46, 0xbfb8aa3b, v44
	v_mul_f32_e32 v47, 0xbfb8aa3b, v45
	v_exp_f32_e32 v46, v46
	v_exp_f32_e32 v47, v47
	v_pk_mul_f32 v[34:35], v[34:35], v[48:49] op_sel_hi:[1,0]
	v_add_f32_e32 v46, 1.0, v46
	v_add_f32_e32 v47, 1.0, v47
	v_rcp_f32_e32 v46, v46
	v_rcp_f32_e32 v47, v47
	s_nop 0
	v_pk_mul_f32 v[44:45], v[44:45], v[46:47]
	s_nop 0
	v_pk_mul_f32 v[42:43], v[42:43], v[44:45]
	s_nop 0
	v_cvt_pk_bf16_f32 v41, v42, v43
	v_mad_i64_i32 v[42:43], s[38:39], v60, s59, v[124:125]
	v_lshl_add_u64 v[44:45], v[42:43], 0, v[126:127]
	global_store_dwordx2 v[44:45], v[40:41], off
	v_mul_f32_e32 v40, 0xbfb8aa3b, v36
	v_mul_f32_e32 v41, 0xbfb8aa3b, v37
	v_exp_f32_e32 v40, v40
	v_exp_f32_e32 v41, v41
	v_add_u32_e32 v44, 0xa0, v142
	v_ashrrev_i32_e32 v45, 31, v44
	v_add_f32_e32 v40, 1.0, v40
	v_add_f32_e32 v41, 1.0, v41
	v_rcp_f32_e32 v40, v40
	v_rcp_f32_e32 v41, v41
	s_nop 0
	v_pk_mul_f32 v[36:37], v[36:37], v[40:41]
	s_nop 0
	v_pk_mul_f32 v[32:33], v[32:33], v[36:37]
	v_pk_mul_f32 v[36:37], v[38:39], v[48:49] op_sel_hi:[1,0]
	v_cvt_pk_bf16_f32 v32, v32, v33
	v_mul_f32_e32 v38, 0xbfb8aa3b, v36
	v_mul_f32_e32 v39, 0xbfb8aa3b, v37
	v_exp_f32_e32 v38, v38
	v_exp_f32_e32 v39, v39
	v_add_f32_e32 v38, 1.0, v38
	v_add_f32_e32 v39, 1.0, v39
	v_rcp_f32_e32 v38, v38
	v_rcp_f32_e32 v39, v39
	s_nop 0
	v_pk_mul_f32 v[36:37], v[36:37], v[38:39]
	s_nop 0
	v_pk_mul_f32 v[34:35], v[34:35], v[36:37]
	s_nop 0
	v_cvt_pk_bf16_f32 v33, v34, v35
	v_lshl_add_u64 v[34:35], v[42:43], 0, v[144:145]
	global_store_dwordx2 v[34:35], v[32:33], off
	v_mov_b32_e32 v32, v252
	v_pk_mul_f32 v[28:29], v[28:29], v[32:33] op_sel_hi:[1,0]
	s_nop 0
	v_mul_f32_e32 v33, 0xbfb8aa3b, v28
	v_exp_f32_e32 v33, v33
	s_nop 0
	v_add_f32_e32 v33, 1.0, v33
	v_rcp_f32_e32 v34, v33
	v_mul_f32_e32 v33, 0xbfb8aa3b, v29
	v_exp_f32_e32 v33, v33
	s_nop 0
	v_add_f32_e32 v33, 1.0, v33
	v_rcp_f32_e32 v35, v33
	v_pk_mul_f32 v[24:25], v[24:25], v[32:33] op_sel_hi:[1,0]
	v_pk_mul_f32 v[26:27], v[26:27], v[32:33] op_sel_hi:[1,0]
	v_pk_mul_f32 v[20:21], v[20:21], v[32:33] op_sel_hi:[1,0]
	v_pk_mul_f32 v[28:29], v[28:29], v[34:35]
	v_pk_mul_f32 v[16:17], v[16:17], v[32:33] op_sel_hi:[1,0]
	v_pk_mul_f32 v[24:25], v[24:25], v[28:29]
	v_pk_mul_f32 v[28:29], v[30:31], v[32:33] op_sel_hi:[1,0]
	v_cvt_pk_bf16_f32 v24, v24, v25
	v_mul_f32_e32 v30, 0xbfb8aa3b, v28
	v_mul_f32_e32 v31, 0xbfb8aa3b, v29
	v_exp_f32_e32 v30, v30
; __device__ __forceinline__ float sigmoidf_(float x) { return __builtin_amdgcn_rcpf(1.f + __expf(-x)); }
; __device__ __forceinline__ u32x2 pack4(const f32x4& a) { u32x2 w; w.x = pk2(a[0], a[1]); w.y = pk2(a[2], a[3]); return w; }
; #define EPI_LOOP_ROWS for (int am_ = 0; am_ < 8; ++am_)
;     __device__ __forceinline__ void operator()(const f32x4 (&acc)[2][2][4][2], const pg8::Unit& u, int wr, int wc, int fr, int fq) const { asm volatile("" : "+v"(fr), "+v"(fq));
;     ...
;         EPI_LOOP_ROWS { EPI_AM const int row = u.pm * 256 + ai * 128 + wr * 64 + m * 16 + fr; const float rstd = ss_rstd(ss + (size_t)row * 16);
; #pragma unroll
;             for (int bj = 0; bj < 2; ++bj) { const int col0 = u.pn * 256 + bj * 128 + wc * 32 + 8 * fq; const f32x4 g = acc[ai][bj][m][0] * rstd, up = acc[ai][bj][m][1] * rstd; f32x4 o;
; #pragma unroll
;                 for (int j = 0; j < 4; ++j) o[j] = g[j] * sigmoidf_(g[j]) * up[j];
;                 *(u32x2*)(act + (size_t)row * FF + (col0 >> 1)) = pack4(o); } }
	v_exp_f32_e32 v31, v31
	v_pk_mul_f32 v[18:19], v[18:19], v[32:33] op_sel_hi:[1,0]
	v_add_f32_e32 v30, 1.0, v30
	v_add_f32_e32 v31, 1.0, v31
	v_rcp_f32_e32 v30, v30
	v_rcp_f32_e32 v31, v31
	s_nop 0
	v_pk_mul_f32 v[28:29], v[28:29], v[30:31]
	s_nop 0
	v_pk_mul_f32 v[26:27], v[26:27], v[28:29]
	s_nop 0
	v_cvt_pk_bf16_f32 v25, v26, v27
	v_mad_i64_i32 v[26:27], s[38:39], v44, s59, v[124:125]
	v_lshl_add_u64 v[28:29], v[26:27], 0, v[126:127]
	global_store_dwordx2 v[28:29], v[24:25], off
	v_mul_f32_e32 v24, 0xbfb8aa3b, v20
	v_mul_f32_e32 v25, 0xbfb8aa3b, v21
	v_exp_f32_e32 v24, v24
	v_exp_f32_e32 v25, v25
	v_add_u32_e32 v28, 0xb0, v142
	v_ashrrev_i32_e32 v29, 31, v28
	v_add_f32_e32 v24, 1.0, v24
	v_add_f32_e32 v25, 1.0, v25
	v_rcp_f32_e32 v24, v24
	v_rcp_f32_e32 v25, v25
	s_nop 0
	v_pk_mul_f32 v[20:21], v[20:21], v[24:25]
	s_nop 0
	v_pk_mul_f32 v[16:17], v[16:17], v[20:21]
	v_pk_mul_f32 v[20:21], v[22:23], v[32:33] op_sel_hi:[1,0]
	v_cvt_pk_bf16_f32 v16, v16, v17
	v_mul_f32_e32 v22, 0xbfb8aa3b, v20
	v_mul_f32_e32 v23, 0xbfb8aa3b, v21
	v_exp_f32_e32 v22, v22
	v_exp_f32_e32 v23, v23
	v_add_f32_e32 v22, 1.0, v22
	v_add_f32_e32 v23, 1.0, v23
	v_rcp_f32_e32 v22, v22
	v_rcp_f32_e32 v23, v23
	s_nop 0
	v_pk_mul_f32 v[20:21], v[20:21], v[22:23]
	s_nop 0
	v_pk_mul_f32 v[18:19], v[18:19], v[20:21]
	s_nop 0
	v_cvt_pk_bf16_f32 v17, v18, v19
	v_lshl_add_u64 v[18:19], v[26:27], 0, v[144:145]
	global_store_dwordx2 v[18:19], v[16:17], off
	v_mov_b32_e32 v16, v253
	v_pk_mul_f32 v[12:13], v[12:13], v[16:17] op_sel_hi:[1,0]
	s_and_b64 vcc, exec, s[2:3]
	v_mul_f32_e32 v17, 0xbfb8aa3b, v12
	v_exp_f32_e32 v17, v17
	s_nop 0
	v_add_f32_e32 v17, 1.0, v17
	v_rcp_f32_e32 v18, v17
	v_mul_f32_e32 v17, 0xbfb8aa3b, v13
	v_exp_f32_e32 v17, v17
	s_nop 0
	v_add_f32_e32 v17, 1.0, v17
	v_rcp_f32_e32 v19, v17
	v_pk_mul_f32 v[8:9], v[8:9], v[16:17] op_sel_hi:[1,0]
	v_pk_mul_f32 v[10:11], v[10:11], v[16:17] op_sel_hi:[1,0]
	v_pk_mul_f32 v[4:5], v[4:5], v[16:17] op_sel_hi:[1,0]
	v_pk_mul_f32 v[12:13], v[12:13], v[18:19]
	v_pk_mul_f32 v[0:1], v[0:1], v[16:17] op_sel_hi:[1,0]
	v_pk_mul_f32 v[8:9], v[8:9], v[12:13]
	v_pk_mul_f32 v[12:13], v[14:15], v[16:17] op_sel_hi:[1,0]
	v_cvt_pk_bf16_f32 v8, v8, v9
	v_mul_f32_e32 v14, 0xbfb8aa3b, v12
	v_mul_f32_e32 v15, 0xbfb8aa3b, v13
	v_exp_f32_e32 v14, v14
	v_exp_f32_e32 v15, v15
	v_pk_mul_f32 v[2:3], v[2:3], v[16:17] op_sel_hi:[1,0]
	v_add_f32_e32 v14, 1.0, v14
	v_add_f32_e32 v15, 1.0, v15
	v_rcp_f32_e32 v14, v14
	v_rcp_f32_e32 v15, v15
	s_nop 0
	v_pk_mul_f32 v[12:13], v[12:13], v[14:15]
	s_nop 0
	v_pk_mul_f32 v[10:11], v[10:11], v[12:13]
	s_nop 0
	v_cvt_pk_bf16_f32 v9, v10, v11
	v_mad_i64_i32 v[10:11], s[38:39], v28, s59, v[124:125]
	v_lshl_add_u64 v[12:13], v[10:11], 0, v[126:127]
	global_store_dwordx2 v[12:13], v[8:9], off
	v_mul_f32_e32 v8, 0xbfb8aa3b, v4
	v_mul_f32_e32 v9, 0xbfb8aa3b, v5
	v_exp_f32_e32 v8, v8
	v_exp_f32_e32 v9, v9
	s_mov_b64 s[38:39], -1
	v_add_f32_e32 v8, 1.0, v8
	v_add_f32_e32 v9, 1.0, v9
	v_rcp_f32_e32 v8, v8
	v_rcp_f32_e32 v9, v9
	s_nop 0
	v_pk_mul_f32 v[4:5], v[4:5], v[8:9]
	s_nop 0
	v_pk_mul_f32 v[0:1], v[0:1], v[4:5]
	v_pk_mul_f32 v[4:5], v[6:7], v[16:17] op_sel_hi:[1,0]
	v_cvt_pk_bf16_f32 v0, v0, v1
	v_mul_f32_e32 v6, 0xbfb8aa3b, v4
	v_mul_f32_e32 v7, 0xbfb8aa3b, v5
	v_exp_f32_e32 v6, v6
	v_exp_f32_e32 v7, v7
	v_add_f32_e32 v6, 1.0, v6
	v_add_f32_e32 v7, 1.0, v7
	v_rcp_f32_e32 v6, v6
	v_rcp_f32_e32 v7, v7
	s_nop 0
	v_pk_mul_f32 v[4:5], v[4:5], v[6:7]
	s_nop 0
	v_pk_mul_f32 v[2:3], v[2:3], v[4:5]
	s_nop 0
	v_cvt_pk_bf16_f32 v1, v2, v3
	v_lshl_add_u64 v[2:3], v[10:11], 0, v[144:145]
	global_store_dwordx2 v[2:3], v[0:1], off
	s_cbranch_vccnz .LBB0_179
	s_andn2_b64 vcc, exec, s[14:15]
	s_cbranch_vccnz .LBB0_178
	s_barrier
	s_branch .LBB0_178
